# fused attention bodies: s_setprio 1 around the MFMA bursts (QK of both tiles, PV of tile B)
# speedup vs baseline: 1.0081x; 1.0031x over previous
; #define LAS __attribute__((address_space(3)))
; DI float ex2(float x) { return __builtin_amdgcn_exp2f(x); }
; template <int MODE>
; DI void sub_tile(const bf16x8 (&kf)[4], const bf16x8 (&vf)[2][2], const bf16x8 (&qf)[4], f32x16& o0, f32x16& o1, float& l, bool diag, float offs, float fm, const LAS float* fsp, int r, int h) {
;     ...
;         x = qk_tile(kf, qf);
; #pragma unroll
;         for (int g = 0; g < 4; ++g) {
;             const f32x4 fs = *(const LAS f32x4*)(fsp + 16 * (g >> 1) + 8 * h + 4 * (g & 1));
; #pragma unroll
;             for (int e = 0; e < 4; ++e) p[4 * g + e] = ex2(x[4 * g + e] + (fm - fs[e]));
;         }
;     }
;     if (diag) {
; #pragma unroll
;         for (int i = 0; i < 16; ++i) if (kidx(i, h) > r) p[i] = 0.f;
;     }
; #pragma unroll
;     for (int i = 0; i < 16; ++i) l += p[i];
;     pv_tile(o0, o1, vf, p);
; template <int MODE>
; DI void attn_wg2_item(const bf16_t* Qm, const bf16_t* Km, const bf16_t* Vtm, const float* Fb, const float* KMPb, const bf16_t* G, bf16_t* Y, int bh, int qb2, int halfq, int mixer, float Mb, LAS unsigned char* lds, int tid, int wave, int lane) {
;     ...
;                 bf16x8 kf[4], vf[2][2];
; #pragma unroll
;                 for (int sp = 0; sp < 4; ++sp) kf[sp] = *(LAS bf16x8*)(lb + kra + kk * 32 * 144 + sp * 32);
; #pragma unroll
;                 for (int dd = 0; dd < 2; ++dd)
; #pragma unroll
;                     for (int s = 0; s < 2; ++s) vf[dd][s] = *(LAS bf16x8*)(lb + vra + dd * 32 * 144 + kk * 64 + s * 32);
;                 float offA = mb2, offB = mb2;
;                 if (MODE == 2) { offA = ((nb == qblkA) || ((selA >> nb) & 1u)) ? mb2 : NEGI; offB = ((nb == qblkB) || ((selB >> nb) & 1u)) ? mb2 : NEGI; }
;                 const LAS float* fsp = (const LAS float*)(lb + AW_F) + kk * 32;
;                 if (actA) sub_tile<MODE>(kf, vf, qfA, oA0, oA1, lA, tau == qtA, offA, fmA, fsp, r, h);
;                 if (actB) sub_tile<MODE>(kf, vf, qfB, oB0, oB1, lB, tau == qtB, offB, fmB, fsp, r, h);
.LBB0_331:
	s_mul_i32 s5, s85, 0x4900
	s_add_i32 s50, s5, 0
	s_lshl_b32 s5, s64, 1
	s_cmp_lt_i32 s5, s69
	s_cselect_b64 s[66:67], -1, 0
	s_cmp_lt_i32 s5, s84
	s_cselect_b64 s[64:65], -1, 0
	v_add_u32_e32 v0, s50, v192
	v_add_u32_e32 v15, s50, v196
	s_or_b64 s[78:79], s[66:67], s[64:65]
	s_andn2_b64 vcc, exec, s[78:79]
	v_add_u32_e32 v14, v0, v194
	v_add_u32_e32 v0, v15, v194
	s_cbranch_vccnz .LBB0_340
	ds_read_b128 v[144:147], v14 offset:4608
	ds_read_b128 v[148:151], v14 offset:4640
	ds_read_b128 v[152:155], v14 offset:4672
	ds_read_b128 v[156:159], v14 offset:4704
	ds_read_b128 v[140:143], v0 offset:9280
	ds_read_b128 v[136:139], v0 offset:9312
	ds_read_b128 v[132:135], v0 offset:13888
	ds_read_b128 v[128:131], v0 offset:13920
	s_and_b64 s[78:79], s[66:67], s[64:65]
	s_cbranch_scc0 .Lfox_nf1
	s_or_b32 s78, s5, 1
	s_cmp_eq_u32 s78, s69
	s_cbranch_scc1 .Lfox_nf1
	s_cmp_eq_u32 s78, s84
	s_cbranch_scc1 .Lfox_nf1
	v_add_u32_e32 v179, s50, v197
	ds_read_b128 v[200:203], v179 offset:18560
	ds_read_b128 v[204:207], v179 offset:18576
	ds_read_b128 v[208:211], v179 offset:18624
	ds_read_b128 v[212:215], v179 offset:18640
	s_waitcnt lgkmcnt(0)
	v_sub_f32_e32 v80, v188, v200
	v_sub_f32_e32 v81, v188, v201
	v_sub_f32_e32 v82, v188, v202
	v_sub_f32_e32 v83, v188, v203
	v_sub_f32_e32 v84, v188, v204
	v_sub_f32_e32 v85, v188, v205
	v_sub_f32_e32 v86, v188, v206
	v_sub_f32_e32 v87, v188, v207
	v_sub_f32_e32 v88, v188, v208
	v_sub_f32_e32 v89, v188, v209
	v_sub_f32_e32 v90, v188, v210
	v_sub_f32_e32 v91, v188, v211
	v_sub_f32_e32 v92, v188, v212
	v_sub_f32_e32 v93, v188, v213
	v_sub_f32_e32 v94, v188, v214
	v_sub_f32_e32 v95, v188, v215
	s_nop 1
	s_setprio 1
	v_mfma_f32_32x32x16_bf16 v[80:95], v[144:147], v[96:99], v[80:95]
	v_mfma_f32_32x32x16_bf16 v[80:95], v[148:151], v[100:103], v[80:95]
	v_mfma_f32_32x32x16_bf16 v[80:95], v[152:155], v[104:107], v[80:95]
	v_mfma_f32_32x32x16_bf16 v[80:95], v[156:159], v[108:111], v[80:95]
	s_setprio 0
	v_sub_f32_e32 v220, v190, v200
	v_sub_f32_e32 v221, v190, v201
	v_sub_f32_e32 v222, v190, v202
	v_sub_f32_e32 v223, v190, v203
	v_sub_f32_e32 v224, v190, v204
	v_sub_f32_e32 v225, v190, v205
	v_sub_f32_e32 v226, v190, v206
	v_sub_f32_e32 v227, v190, v207
	v_sub_f32_e32 v228, v190, v208
	v_sub_f32_e32 v229, v190, v209
	v_sub_f32_e32 v230, v190, v210
	v_sub_f32_e32 v231, v190, v211
	v_sub_f32_e32 v232, v190, v212
	v_sub_f32_e32 v233, v190, v213
	v_sub_f32_e32 v234, v190, v214
	v_sub_f32_e32 v235, v190, v215
	s_nop 1
	s_setprio 1
	v_mfma_f32_32x32x16_bf16 v[220:235], v[144:147], v[112:115], v[220:235]
	v_mfma_f32_32x32x16_bf16 v[220:235], v[148:151], v[116:119], v[220:235]
	v_mfma_f32_32x32x16_bf16 v[220:235], v[152:155], v[120:123], v[220:235]
	v_mfma_f32_32x32x16_bf16 v[220:235], v[156:159], v[124:127], v[220:235]
	s_setprio 0
	v_exp_f32_e32 v80, v80
	v_exp_f32_e32 v81, v81
	v_exp_f32_e32 v82, v82
	v_exp_f32_e32 v83, v83
	v_exp_f32_e32 v84, v84
	v_exp_f32_e32 v85, v85
	v_exp_f32_e32 v86, v86
	v_exp_f32_e32 v87, v87
	v_exp_f32_e32 v88, v88
	v_exp_f32_e32 v89, v89
	v_exp_f32_e32 v90, v90
	v_exp_f32_e32 v91, v91
	v_exp_f32_e32 v92, v92
	v_exp_f32_e32 v93, v93
	v_exp_f32_e32 v94, v94
	v_exp_f32_e32 v95, v95
	v_exp_f32_e32 v220, v220
	v_add_f32_e32 v198, v80, v198
	v_exp_f32_e32 v221, v221
	v_add_f32_e32 v198, v81, v198
	v_exp_f32_e32 v222, v222
	v_add_f32_e32 v198, v82, v198
	v_exp_f32_e32 v223, v223
	v_add_f32_e32 v198, v83, v198
	v_exp_f32_e32 v224, v224
	v_add_f32_e32 v198, v84, v198
	v_exp_f32_e32 v225, v225
	v_add_f32_e32 v198, v85, v198
	v_exp_f32_e32 v226, v226
	v_add_f32_e32 v198, v86, v198
	v_exp_f32_e32 v227, v227
	v_add_f32_e32 v198, v87, v198
	v_exp_f32_e32 v228, v228
	v_add_f32_e32 v198, v88, v198
	v_exp_f32_e32 v229, v229
	v_add_f32_e32 v198, v89, v198
	v_exp_f32_e32 v230, v230
	v_add_f32_e32 v198, v90, v198
	v_exp_f32_e32 v231, v231
	v_add_f32_e32 v198, v91, v198
	v_exp_f32_e32 v232, v232
	v_add_f32_e32 v198, v92, v198
	v_exp_f32_e32 v233, v233
	v_add_f32_e32 v198, v93, v198
	v_exp_f32_e32 v234, v234
	v_add_f32_e32 v198, v94, v198
	v_exp_f32_e32 v235, v235
	v_add_f32_e32 v198, v95, v198
	v_cvt_pk_bf16_f32 v80, v80, v81
	v_cvt_pk_bf16_f32 v81, v82, v83
	v_cvt_pk_bf16_f32 v82, v84, v85
	v_cvt_pk_bf16_f32 v83, v86, v87
	v_cvt_pk_bf16_f32 v84, v88, v89
	v_cvt_pk_bf16_f32 v85, v90, v91
	v_cvt_pk_bf16_f32 v86, v92, v93
	v_cvt_pk_bf16_f32 v87, v94, v95
	v_mfma_f32_32x32x16_bf16 v[64:79], v[140:143], v[80:83], v[64:79]
	v_add_f32_e32 v175, v220, v175
	v_add_f32_e32 v175, v221, v175
	v_add_f32_e32 v175, v222, v175
	v_add_f32_e32 v175, v223, v175
	v_mfma_f32_32x32x16_bf16 v[48:63], v[132:135], v[80:83], v[48:63]
	v_add_f32_e32 v175, v224, v175
	v_add_f32_e32 v175, v225, v175
	v_add_f32_e32 v175, v226, v175
	v_add_f32_e32 v175, v227, v175
	v_mfma_f32_32x32x16_bf16 v[64:79], v[136:139], v[84:87], v[64:79]
	v_add_f32_e32 v175, v228, v175
	v_add_f32_e32 v175, v229, v175
	v_add_f32_e32 v175, v230, v175
	v_add_f32_e32 v175, v231, v175
	v_mfma_f32_32x32x16_bf16 v[48:63], v[128:131], v[84:87], v[48:63]
	v_add_f32_e32 v175, v232, v175
	v_add_f32_e32 v175, v233, v175
	v_add_f32_e32 v175, v234, v175
	v_add_f32_e32 v175, v235, v175
	v_cvt_pk_bf16_f32 v220, v220, v221
	v_cvt_pk_bf16_f32 v221, v222, v223
	v_cvt_pk_bf16_f32 v222, v224, v225
	v_cvt_pk_bf16_f32 v223, v226, v227
	v_cvt_pk_bf16_f32 v224, v228, v229
	v_cvt_pk_bf16_f32 v225, v230, v231
	v_cvt_pk_bf16_f32 v226, v232, v233
	v_cvt_pk_bf16_f32 v227, v234, v235
	s_setprio 1
	v_mfma_f32_32x32x16_bf16 v[32:47], v[140:143], v[220:223], v[32:47]
	v_mfma_f32_32x32x16_bf16 v[16:31], v[132:135], v[220:223], v[16:31]
	v_mfma_f32_32x32x16_bf16 v[32:47], v[136:139], v[224:227], v[32:47]
	v_mfma_f32_32x32x16_bf16 v[16:31], v[128:131], v[224:227], v[16:31]
	s_setprio 0
	s_branch .LBB0_340

; #define LAS __attribute__((address_space(3)))
; DI float ex2(float x) { return __builtin_amdgcn_exp2f(x); }
; template <int MODE>
; DI void sub_tile(const bf16x8 (&kf)[4], const bf16x8 (&vf)[2][2], const bf16x8 (&qf)[4], f32x16& o0, f32x16& o1, float& l, bool diag, float offs, float fm, const LAS float* fsp, int r, int h) {
;     ...
;         x = qk_tile(kf, qf);
; #pragma unroll
;         for (int g = 0; g < 4; ++g) {
;             const f32x4 fs = *(const LAS f32x4*)(fsp + 16 * (g >> 1) + 8 * h + 4 * (g & 1));
; #pragma unroll
;             for (int e = 0; e < 4; ++e) p[4 * g + e] = ex2(x[4 * g + e] + (fm - fs[e]));
;         }
;     }
;     if (diag) {
; #pragma unroll
;         for (int i = 0; i < 16; ++i) if (kidx(i, h) > r) p[i] = 0.f;
;     }
; #pragma unroll
;     for (int i = 0; i < 16; ++i) l += p[i];
;     pv_tile(o0, o1, vf, p);
; template <int MODE>
; DI void attn_wg2_item(const bf16_t* Qm, const bf16_t* Km, const bf16_t* Vtm, const float* Fb, const float* KMPb, const bf16_t* G, bf16_t* Y, int bh, int qb2, int halfq, int mixer, float Mb, LAS unsigned char* lds, int tid, int wave, int lane) {
;     ...
;                 bf16x8 kf[4], vf[2][2];
; #pragma unroll
;                 for (int sp = 0; sp < 4; ++sp) kf[sp] = *(LAS bf16x8*)(lb + kra + kk * 32 * 144 + sp * 32);
; #pragma unroll
;                 for (int dd = 0; dd < 2; ++dd)
; #pragma unroll
;                     for (int s = 0; s < 2; ++s) vf[dd][s] = *(LAS bf16x8*)(lb + vra + dd * 32 * 144 + kk * 64 + s * 32);
;                 float offA = mb2, offB = mb2;
;                 if (MODE == 2) { offA = ((nb == qblkA) || ((selA >> nb) & 1u)) ? mb2 : NEGI; offB = ((nb == qblkB) || ((selB >> nb) & 1u)) ? mb2 : NEGI; }
;                 const LAS float* fsp = (const LAS float*)(lb + AW_F) + kk * 32;
;                 if (actA) sub_tile<MODE>(kf, vf, qfA, oA0, oA1, lA, tau == qtA, offA, fmA, fsp, r, h);
;                 if (actB) sub_tile<MODE>(kf, vf, qfB, oB0, oB1, lB, tau == qtB, offB, fmB, fsp, r, h);
.LBB0_340:
	s_cmp_le_i32 s5, s69
	s_cselect_b64 s[66:67], -1, 0
	s_cmp_le_i32 s5, s84
	s_cselect_b64 s[64:65], -1, 0
	s_or_b64 s[78:79], s[66:67], s[64:65]
	s_andn2_b64 vcc, exec, s[78:79]
	s_cbranch_vccnz .LBB0_349
	s_waitcnt lgkmcnt(4)
	ds_read_b128 v[156:159], v14
	ds_read_b128 v[144:147], v14 offset:32
	ds_read_b128 v[148:151], v14 offset:64
	ds_read_b128 v[152:155], v14 offset:96
	s_waitcnt lgkmcnt(7)
	ds_read_b128 v[140:143], v0 offset:9216
	s_waitcnt lgkmcnt(7)
	ds_read_b128 v[136:139], v0 offset:9248
	s_waitcnt lgkmcnt(7)
	ds_read_b128 v[132:135], v0 offset:13824
	s_waitcnt lgkmcnt(7)
	ds_read_b128 v[128:131], v0 offset:13856
	s_and_b64 s[78:79], s[66:67], s[64:65]
	s_cbranch_scc0 .Lfox_nf0
	s_cmp_eq_u32 s5, s69
	s_cbranch_scc1 .Lfox_nf0
	s_cmp_eq_u32 s5, s84
	s_cbranch_scc1 .Lfox_nf0
	v_add_u32_e32 v0, s50, v197
	ds_read_b128 v[200:203], v0 offset:18432
	ds_read_b128 v[204:207], v0 offset:18448
	ds_read_b128 v[208:211], v0 offset:18496
	ds_read_b128 v[212:215], v0 offset:18512
	s_waitcnt lgkmcnt(0)
	v_sub_f32_e32 v80, v188, v200
	v_sub_f32_e32 v81, v188, v201
	v_sub_f32_e32 v82, v188, v202
	v_sub_f32_e32 v83, v188, v203
	v_sub_f32_e32 v84, v188, v204
	v_sub_f32_e32 v85, v188, v205
	v_sub_f32_e32 v86, v188, v206
	v_sub_f32_e32 v87, v188, v207
	v_sub_f32_e32 v88, v188, v208
	v_sub_f32_e32 v89, v188, v209
	v_sub_f32_e32 v90, v188, v210
	v_sub_f32_e32 v91, v188, v211
	v_sub_f32_e32 v92, v188, v212
	v_sub_f32_e32 v93, v188, v213
	v_sub_f32_e32 v94, v188, v214
	v_sub_f32_e32 v95, v188, v215
	s_nop 1
	s_setprio 1
	v_mfma_f32_32x32x16_bf16 v[80:95], v[156:159], v[96:99], v[80:95]
	v_mfma_f32_32x32x16_bf16 v[80:95], v[144:147], v[100:103], v[80:95]
	v_mfma_f32_32x32x16_bf16 v[80:95], v[148:151], v[104:107], v[80:95]
	v_mfma_f32_32x32x16_bf16 v[80:95], v[152:155], v[108:111], v[80:95]
	s_setprio 0
	v_sub_f32_e32 v220, v190, v200
	v_sub_f32_e32 v221, v190, v201
	v_sub_f32_e32 v222, v190, v202
	v_sub_f32_e32 v223, v190, v203
	v_sub_f32_e32 v224, v190, v204
	v_sub_f32_e32 v225, v190, v205
	v_sub_f32_e32 v226, v190, v206
	v_sub_f32_e32 v227, v190, v207
	v_sub_f32_e32 v228, v190, v208
	v_sub_f32_e32 v229, v190, v209
	v_sub_f32_e32 v230, v190, v210
	v_sub_f32_e32 v231, v190, v211
	v_sub_f32_e32 v232, v190, v212
	v_sub_f32_e32 v233, v190, v213
	v_sub_f32_e32 v234, v190, v214
	v_sub_f32_e32 v235, v190, v215
	s_nop 1
	s_setprio 1
	v_mfma_f32_32x32x16_bf16 v[220:235], v[156:159], v[112:115], v[220:235]
	v_mfma_f32_32x32x16_bf16 v[220:235], v[144:147], v[116:119], v[220:235]
	v_mfma_f32_32x32x16_bf16 v[220:235], v[148:151], v[120:123], v[220:235]
	v_mfma_f32_32x32x16_bf16 v[220:235], v[152:155], v[124:127], v[220:235]
	s_setprio 0
	v_exp_f32_e32 v80, v80
	v_exp_f32_e32 v81, v81
	v_exp_f32_e32 v82, v82
	v_exp_f32_e32 v83, v83
	v_exp_f32_e32 v84, v84
	v_exp_f32_e32 v85, v85
	v_exp_f32_e32 v86, v86
	v_exp_f32_e32 v87, v87
	v_exp_f32_e32 v88, v88
	v_exp_f32_e32 v89, v89
	v_exp_f32_e32 v90, v90
	v_exp_f32_e32 v91, v91
	v_exp_f32_e32 v92, v92
	v_exp_f32_e32 v93, v93
	v_exp_f32_e32 v94, v94
	v_exp_f32_e32 v95, v95
	v_exp_f32_e32 v220, v220
	v_add_f32_e32 v198, v80, v198
	v_exp_f32_e32 v221, v221
	v_add_f32_e32 v198, v81, v198
	v_exp_f32_e32 v222, v222
	v_add_f32_e32 v198, v82, v198
	v_exp_f32_e32 v223, v223
	v_add_f32_e32 v198, v83, v198
	v_exp_f32_e32 v224, v224
	v_add_f32_e32 v198, v84, v198
	v_exp_f32_e32 v225, v225
	v_add_f32_e32 v198, v85, v198
	v_exp_f32_e32 v226, v226
	v_add_f32_e32 v198, v86, v198
	v_exp_f32_e32 v227, v227
	v_add_f32_e32 v198, v87, v198
	v_exp_f32_e32 v228, v228
	v_add_f32_e32 v198, v88, v198
	v_exp_f32_e32 v229, v229
	v_add_f32_e32 v198, v89, v198
	v_exp_f32_e32 v230, v230
	v_add_f32_e32 v198, v90, v198
	v_exp_f32_e32 v231, v231
	v_add_f32_e32 v198, v91, v198
	v_exp_f32_e32 v232, v232
	v_add_f32_e32 v198, v92, v198
	v_exp_f32_e32 v233, v233
	v_add_f32_e32 v198, v93, v198
	v_exp_f32_e32 v234, v234
	v_add_f32_e32 v198, v94, v198
	v_exp_f32_e32 v235, v235
	v_add_f32_e32 v198, v95, v198
	v_cvt_pk_bf16_f32 v80, v80, v81
	v_cvt_pk_bf16_f32 v81, v82, v83
	v_cvt_pk_bf16_f32 v82, v84, v85
	v_cvt_pk_bf16_f32 v83, v86, v87
	v_cvt_pk_bf16_f32 v84, v88, v89
	v_cvt_pk_bf16_f32 v85, v90, v91
	v_cvt_pk_bf16_f32 v86, v92, v93
	v_cvt_pk_bf16_f32 v87, v94, v95
	v_mfma_f32_32x32x16_bf16 v[64:79], v[140:143], v[80:83], v[64:79]
	v_add_f32_e32 v175, v220, v175
	v_add_f32_e32 v175, v221, v175
	v_add_f32_e32 v175, v222, v175
	v_add_f32_e32 v175, v223, v175
	v_mfma_f32_32x32x16_bf16 v[48:63], v[132:135], v[80:83], v[48:63]
	v_add_f32_e32 v175, v224, v175
	v_add_f32_e32 v175, v225, v175
	v_add_f32_e32 v175, v226, v175
	v_add_f32_e32 v175, v227, v175
	v_mfma_f32_32x32x16_bf16 v[64:79], v[136:139], v[84:87], v[64:79]
	v_add_f32_e32 v175, v228, v175
	v_add_f32_e32 v175, v229, v175
	v_add_f32_e32 v175, v230, v175
	v_add_f32_e32 v175, v231, v175
	v_mfma_f32_32x32x16_bf16 v[48:63], v[128:131], v[84:87], v[48:63]
	v_add_f32_e32 v175, v232, v175
	v_add_f32_e32 v175, v233, v175
	v_add_f32_e32 v175, v234, v175
	v_add_f32_e32 v175, v235, v175
	v_cvt_pk_bf16_f32 v220, v220, v221
	v_cvt_pk_bf16_f32 v221, v222, v223
	v_cvt_pk_bf16_f32 v222, v224, v225
	v_cvt_pk_bf16_f32 v223, v226, v227
	v_cvt_pk_bf16_f32 v224, v228, v229
	v_cvt_pk_bf16_f32 v225, v230, v231
	v_cvt_pk_bf16_f32 v226, v232, v233
	v_cvt_pk_bf16_f32 v227, v234, v235
	s_setprio 1
	v_mfma_f32_32x32x16_bf16 v[32:47], v[140:143], v[220:223], v[32:47]
	v_mfma_f32_32x32x16_bf16 v[16:31], v[132:135], v[220:223], v[16:31]
	v_mfma_f32_32x32x16_bf16 v[32:47], v[136:139], v[224:227], v[32:47]
	v_mfma_f32_32x32x16_bf16 v[16:31], v[128:131], v[224:227], v[16:31]
	s_setprio 0
	s_branch .LBB0_349

; #define LAS __attribute__((address_space(3)))
; DI f32x16 mfma32(bf16x8 a, bf16x8 b, f32x16 c) { return __builtin_amdgcn_mfma_f32_32x32x16_bf16(a, b, c, 0, 0, 0); }
; DI float ex2(float x) { return __builtin_amdgcn_exp2f(x); }
; template <int MODE>
; DI void sub_tile(const bf16x8 (&kf)[4], const bf16x8 (&vf)[2][2], const bf16x8 (&qf)[4], f32x16& o0, f32x16& o1, float& l, bool diag, float offs, float fm, const LAS float* fsp, int r, int h) {
;     ...
;     if (MODE == 2) {
; #pragma unroll
;         for (int i = 0; i < 16; ++i) x[i] = offs;
; #pragma unroll
;         for (int sp = 0; sp < 4; ++sp) x = mfma32(kf[sp], qf[sp], x);
; #pragma unroll
;         for (int i = 0; i < 16; ++i) p[i] = ex2(x[i]);
; template <int MODE>
; DI void attn_wg2_item(const bf16_t* Qm, const bf16_t* Km, const bf16_t* Vtm, const float* Fb, const float* KMPb, const bf16_t* G, bf16_t* Y, int bh, int qb2, int halfq, int mixer, float Mb, LAS unsigned char* lds, int tid, int wave, int lane) {
;     ...
;                 bf16x8 kf[4], vf[2][2];
; #pragma unroll
;                 for (int sp = 0; sp < 4; ++sp) kf[sp] = *(LAS bf16x8*)(lb + kra + kk * 32 * 144 + sp * 32);
; #pragma unroll
;                 for (int dd = 0; dd < 2; ++dd)
; #pragma unroll
;                     for (int s = 0; s < 2; ++s) vf[dd][s] = *(LAS bf16x8*)(lb + vra + dd * 32 * 144 + kk * 64 + s * 32);
;                 float offA = mb2, offB = mb2;
;                 if (MODE == 2) { offA = ((nb == qblkA) || ((selA >> nb) & 1u)) ? mb2 : NEGI; offB = ((nb == qblkB) || ((selB >> nb) & 1u)) ? mb2 : NEGI; }
;                 const LAS float* fsp = (const LAS float*)(lb + AW_F) + kk * 32;
;                 if (actA) sub_tile<MODE>(kf, vf, qfA, oA0, oA1, lA, tau == qtA, offA, fmA, fsp, r, h);
;                 if (actB) sub_tile<MODE>(kf, vf, qfB, oB0, oB1, lB, tau == qtB, offB, fmB, fsp, r, h);
.LBB0_393:
	s_mul_i32 s47, s79, 0x4900
	s_add_i32 s47, s47, 0
	s_lshl_b32 s87, s46, 1
	s_lshr_b32 s88, s46, 2
	s_cmp_lt_i32 s87, s84
	v_add_u32_e32 v0, s47, v175
	v_add_u32_e32 v10, s47, v173
	s_cselect_b64 s[46:47], -1, 0
	s_cmp_lt_i32 s87, s85
	s_cselect_b64 s[64:65], -1, 0
	s_lshl_b32 s89, 1, s88
	v_and_b32_e32 v11, s89, v176
	v_cmp_ne_u32_e32 vcc, 0, v11
	v_and_b32_e32 v11, s89, v177
	s_and_b64 s[48:49], s[46:47], vcc
	v_cmp_ne_u32_e64 s[46:47], 0, v11
	s_and_b64 s[66:67], s[64:65], s[46:47]
	s_or_b64 s[68:69], s[48:49], s[66:67]
	v_add_u32_e32 v14, v0, v172
	v_add_u32_e32 v0, v10, v172
	s_and_saveexec_b64 s[64:65], s[68:69]
	s_cbranch_execz .LBB0_403
	ds_read_b128 v[152:155], v14 offset:4608
	ds_read_b128 v[148:151], v14 offset:4640
	ds_read_b128 v[144:147], v14 offset:4672
	ds_read_b128 v[140:143], v14 offset:4704
	ds_read_b128 v[136:139], v0 offset:9280
	ds_read_b128 v[132:135], v0 offset:9312
	ds_read_b128 v[128:131], v0 offset:13888
	ds_read_b128 v[10:13], v0 offset:13920
	s_or_b32 s90, s87, 1
	s_and_b64 s[92:93], s[48:49], s[66:67]
	s_cbranch_scc0 .Lmoba_nf1
	s_cmp_eq_u32 s90, s84
	s_cbranch_scc1 .Lmoba_nf1
	s_cmp_eq_u32 s90, s85
	s_cbranch_scc1 .Lmoba_nf1
	s_waitcnt lgkmcnt(4)
	s_setprio 1
	v_mfma_f32_32x32x16_bf16 v[80:95], v[152:155], v[96:99], v[196:211]
	v_mfma_f32_32x32x16_bf16 v[80:95], v[148:151], v[100:103], v[80:95]
	v_mfma_f32_32x32x16_bf16 v[80:95], v[144:147], v[104:107], v[80:95]
	v_mfma_f32_32x32x16_bf16 v[80:95], v[140:143], v[108:111], v[80:95]
	v_mfma_f32_32x32x16_bf16 v[228:243], v[152:155], v[112:115], v[212:227]
	v_mfma_f32_32x32x16_bf16 v[228:243], v[148:151], v[116:119], v[228:243]
	v_mfma_f32_32x32x16_bf16 v[228:243], v[144:147], v[120:123], v[228:243]
	v_mfma_f32_32x32x16_bf16 v[228:243], v[140:143], v[124:127], v[228:243]
	s_setprio 0
	s_nop 6
	v_exp_f32_e32 v80, v80
	v_exp_f32_e32 v81, v81
	v_exp_f32_e32 v82, v82
	v_exp_f32_e32 v83, v83
	v_exp_f32_e32 v84, v84
	v_exp_f32_e32 v85, v85
	v_exp_f32_e32 v86, v86
	v_exp_f32_e32 v87, v87
	v_exp_f32_e32 v88, v88
	v_exp_f32_e32 v89, v89
	v_exp_f32_e32 v90, v90
	v_exp_f32_e32 v91, v91
	v_exp_f32_e32 v92, v92
	v_exp_f32_e32 v93, v93
	v_exp_f32_e32 v94, v94
	v_exp_f32_e32 v95, v95
	v_exp_f32_e32 v228, v228
	v_add_f32_e32 v186, v80, v186
	v_exp_f32_e32 v229, v229
	v_add_f32_e32 v186, v81, v186
	v_exp_f32_e32 v230, v230
	v_add_f32_e32 v186, v82, v186
	v_exp_f32_e32 v231, v231
	v_add_f32_e32 v186, v83, v186
	v_exp_f32_e32 v232, v232
	v_add_f32_e32 v186, v84, v186
	v_exp_f32_e32 v233, v233
	v_add_f32_e32 v186, v85, v186
	v_exp_f32_e32 v234, v234
	v_add_f32_e32 v186, v86, v186
	v_exp_f32_e32 v235, v235
	v_add_f32_e32 v186, v87, v186
	v_exp_f32_e32 v236, v236
	v_add_f32_e32 v186, v88, v186
	v_exp_f32_e32 v237, v237
	v_add_f32_e32 v186, v89, v186
	v_exp_f32_e32 v238, v238
	v_add_f32_e32 v186, v90, v186
	v_exp_f32_e32 v239, v239
	v_add_f32_e32 v186, v91, v186
	v_exp_f32_e32 v240, v240
	v_add_f32_e32 v186, v92, v186
	v_exp_f32_e32 v241, v241
	v_add_f32_e32 v186, v93, v186
	v_exp_f32_e32 v242, v242
	v_add_f32_e32 v186, v94, v186
	v_exp_f32_e32 v243, v243
	v_add_f32_e32 v186, v95, v186
	s_waitcnt lgkmcnt(0)
	v_cvt_pk_bf16_f32 v80, v80, v81
	v_cvt_pk_bf16_f32 v81, v82, v83
	v_cvt_pk_bf16_f32 v82, v84, v85
	v_cvt_pk_bf16_f32 v83, v86, v87
	v_cvt_pk_bf16_f32 v84, v88, v89
	v_cvt_pk_bf16_f32 v85, v90, v91
	v_cvt_pk_bf16_f32 v86, v92, v93
	v_cvt_pk_bf16_f32 v87, v94, v95
	v_mfma_f32_32x32x16_bf16 v[64:79], v[136:139], v[80:83], v[64:79]
	v_add_f32_e32 v170, v228, v170
	v_add_f32_e32 v170, v229, v170
	v_add_f32_e32 v170, v230, v170
	v_add_f32_e32 v170, v231, v170
	v_mfma_f32_32x32x16_bf16 v[48:63], v[128:131], v[80:83], v[48:63]
	v_add_f32_e32 v170, v232, v170
	v_add_f32_e32 v170, v233, v170
	v_add_f32_e32 v170, v234, v170
	v_add_f32_e32 v170, v235, v170
	v_mfma_f32_32x32x16_bf16 v[64:79], v[132:135], v[84:87], v[64:79]
	v_add_f32_e32 v170, v236, v170
	v_add_f32_e32 v170, v237, v170
	v_add_f32_e32 v170, v238, v170
	v_add_f32_e32 v170, v239, v170
	v_mfma_f32_32x32x16_bf16 v[48:63], v[10:13], v[84:87], v[48:63]
	v_add_f32_e32 v170, v240, v170
	v_add_f32_e32 v170, v241, v170
	v_add_f32_e32 v170, v242, v170
	v_add_f32_e32 v170, v243, v170
	v_cvt_pk_bf16_f32 v228, v228, v229
	v_cvt_pk_bf16_f32 v229, v230, v231
	v_cvt_pk_bf16_f32 v230, v232, v233
	v_cvt_pk_bf16_f32 v231, v234, v235
	v_cvt_pk_bf16_f32 v232, v236, v237
	v_cvt_pk_bf16_f32 v233, v238, v239
	v_cvt_pk_bf16_f32 v234, v240, v241
	v_cvt_pk_bf16_f32 v235, v242, v243
	s_setprio 1
	v_mfma_f32_32x32x16_bf16 v[32:47], v[136:139], v[228:231], v[32:47]
	v_mfma_f32_32x32x16_bf16 v[16:31], v[128:131], v[228:231], v[16:31]
	v_mfma_f32_32x32x16_bf16 v[32:47], v[132:135], v[232:235], v[32:47]
	v_mfma_f32_32x32x16_bf16 v[16:31], v[10:13], v[232:235], v[16:31]
	s_setprio 0
	s_branch .LBB0_403

; #define LAS __attribute__((address_space(3)))
; DI f32x16 mfma32(bf16x8 a, bf16x8 b, f32x16 c) { return __builtin_amdgcn_mfma_f32_32x32x16_bf16(a, b, c, 0, 0, 0); }
; DI float ex2(float x) { return __builtin_amdgcn_exp2f(x); }
; template <int MODE>
; DI void sub_tile(const bf16x8 (&kf)[4], const bf16x8 (&vf)[2][2], const bf16x8 (&qf)[4], f32x16& o0, f32x16& o1, float& l, bool diag, float offs, float fm, const LAS float* fsp, int r, int h) {
;     ...
;     if (MODE == 2) {
; #pragma unroll
;         for (int i = 0; i < 16; ++i) x[i] = offs;
; #pragma unroll
;         for (int sp = 0; sp < 4; ++sp) x = mfma32(kf[sp], qf[sp], x);
; #pragma unroll
;         for (int i = 0; i < 16; ++i) p[i] = ex2(x[i]);
; template <int MODE>
; DI void attn_wg2_item(const bf16_t* Qm, const bf16_t* Km, const bf16_t* Vtm, const float* Fb, const float* KMPb, const bf16_t* G, bf16_t* Y, int bh, int qb2, int halfq, int mixer, float Mb, LAS unsigned char* lds, int tid, int wave, int lane) {
;     ...
;                 bf16x8 kf[4], vf[2][2];
; #pragma unroll
;                 for (int sp = 0; sp < 4; ++sp) kf[sp] = *(LAS bf16x8*)(lb + kra + kk * 32 * 144 + sp * 32);
; #pragma unroll
;                 for (int dd = 0; dd < 2; ++dd)
; #pragma unroll
;                     for (int s = 0; s < 2; ++s) vf[dd][s] = *(LAS bf16x8*)(lb + vra + dd * 32 * 144 + kk * 64 + s * 32);
;                 float offA = mb2, offB = mb2;
;                 if (MODE == 2) { offA = ((nb == qblkA) || ((selA >> nb) & 1u)) ? mb2 : NEGI; offB = ((nb == qblkB) || ((selB >> nb) & 1u)) ? mb2 : NEGI; }
;                 const LAS float* fsp = (const LAS float*)(lb + AW_F) + kk * 32;
;                 if (actA) sub_tile<MODE>(kf, vf, qfA, oA0, oA1, lA, tau == qtA, offA, fmA, fsp, r, h);
;                 if (actB) sub_tile<MODE>(kf, vf, qfB, oB0, oB1, lB, tau == qtB, offB, fmB, fsp, r, h);
.LBB0_403:
	s_or_b64 exec, exec, s[64:65]
	s_cmp_le_i32 s87, s84
	s_cselect_b64 s[48:49], -1, 0
	s_cmp_le_i32 s87, s85
	s_cselect_b64 s[64:65], -1, 0
	s_and_b64 s[66:67], s[48:49], vcc
	s_and_b64 s[48:49], s[64:65], s[46:47]
	s_or_b64 s[64:65], s[66:67], s[48:49]
	s_and_saveexec_b64 s[46:47], s[64:65]
	s_cbranch_execz .LBB0_413
	s_waitcnt lgkmcnt(7)
	ds_read_b128 v[152:155], v14
	s_waitcnt lgkmcnt(7)
	ds_read_b128 v[148:151], v14 offset:32
	s_waitcnt lgkmcnt(7)
	ds_read_b128 v[144:147], v14 offset:64
	s_waitcnt lgkmcnt(7)
	ds_read_b128 v[140:143], v14 offset:96
	s_waitcnt lgkmcnt(7)
	ds_read_b128 v[136:139], v0 offset:9216
	s_waitcnt lgkmcnt(7)
	ds_read_b128 v[132:135], v0 offset:9248
	s_waitcnt lgkmcnt(7)
	ds_read_b128 v[128:131], v0 offset:13824
	s_waitcnt lgkmcnt(7)
	ds_read_b128 v[10:13], v0 offset:13856
	s_and_b64 s[92:93], s[48:49], s[66:67]
	s_cbranch_scc0 .Lmoba_nf0
	s_cmp_eq_u32 s87, s84
	s_cbranch_scc1 .Lmoba_nf0
	s_cmp_eq_u32 s87, s85
	s_cbranch_scc1 .Lmoba_nf0
	s_waitcnt lgkmcnt(4)
	s_setprio 1
	v_mfma_f32_32x32x16_bf16 v[80:95], v[152:155], v[96:99], v[196:211]
	v_mfma_f32_32x32x16_bf16 v[80:95], v[148:151], v[100:103], v[80:95]
	v_mfma_f32_32x32x16_bf16 v[80:95], v[144:147], v[104:107], v[80:95]
	v_mfma_f32_32x32x16_bf16 v[80:95], v[140:143], v[108:111], v[80:95]
	v_mfma_f32_32x32x16_bf16 v[228:243], v[152:155], v[112:115], v[212:227]
	v_mfma_f32_32x32x16_bf16 v[228:243], v[148:151], v[116:119], v[228:243]
	v_mfma_f32_32x32x16_bf16 v[228:243], v[144:147], v[120:123], v[228:243]
	v_mfma_f32_32x32x16_bf16 v[228:243], v[140:143], v[124:127], v[228:243]
	s_setprio 0
	s_nop 6
	v_exp_f32_e32 v80, v80
	v_exp_f32_e32 v81, v81
	v_exp_f32_e32 v82, v82
	v_exp_f32_e32 v83, v83
	v_exp_f32_e32 v84, v84
	v_exp_f32_e32 v85, v85
	v_exp_f32_e32 v86, v86
	v_exp_f32_e32 v87, v87
	v_exp_f32_e32 v88, v88
	v_exp_f32_e32 v89, v89
	v_exp_f32_e32 v90, v90
	v_exp_f32_e32 v91, v91
	v_exp_f32_e32 v92, v92
	v_exp_f32_e32 v93, v93
	v_exp_f32_e32 v94, v94
	v_exp_f32_e32 v95, v95
	v_exp_f32_e32 v228, v228
	v_add_f32_e32 v186, v80, v186
	v_exp_f32_e32 v229, v229
	v_add_f32_e32 v186, v81, v186
	v_exp_f32_e32 v230, v230
	v_add_f32_e32 v186, v82, v186
	v_exp_f32_e32 v231, v231
	v_add_f32_e32 v186, v83, v186
	v_exp_f32_e32 v232, v232
	v_add_f32_e32 v186, v84, v186
	v_exp_f32_e32 v233, v233
	v_add_f32_e32 v186, v85, v186
	v_exp_f32_e32 v234, v234
	v_add_f32_e32 v186, v86, v186
	v_exp_f32_e32 v235, v235
	v_add_f32_e32 v186, v87, v186
	v_exp_f32_e32 v236, v236
	v_add_f32_e32 v186, v88, v186
	v_exp_f32_e32 v237, v237
	v_add_f32_e32 v186, v89, v186
	v_exp_f32_e32 v238, v238
	v_add_f32_e32 v186, v90, v186
	v_exp_f32_e32 v239, v239
	v_add_f32_e32 v186, v91, v186
	v_exp_f32_e32 v240, v240
	v_add_f32_e32 v186, v92, v186
	v_exp_f32_e32 v241, v241
	v_add_f32_e32 v186, v93, v186
	v_exp_f32_e32 v242, v242
	v_add_f32_e32 v186, v94, v186
	v_exp_f32_e32 v243, v243
	v_add_f32_e32 v186, v95, v186
	s_waitcnt lgkmcnt(0)
	v_cvt_pk_bf16_f32 v80, v80, v81
	v_cvt_pk_bf16_f32 v81, v82, v83
	v_cvt_pk_bf16_f32 v82, v84, v85
	v_cvt_pk_bf16_f32 v83, v86, v87
	v_cvt_pk_bf16_f32 v84, v88, v89
	v_cvt_pk_bf16_f32 v85, v90, v91
	v_cvt_pk_bf16_f32 v86, v92, v93
	v_cvt_pk_bf16_f32 v87, v94, v95
	v_mfma_f32_32x32x16_bf16 v[64:79], v[136:139], v[80:83], v[64:79]
	v_add_f32_e32 v170, v228, v170
	v_add_f32_e32 v170, v229, v170
	v_add_f32_e32 v170, v230, v170
	v_add_f32_e32 v170, v231, v170
	v_mfma_f32_32x32x16_bf16 v[48:63], v[128:131], v[80:83], v[48:63]
	v_add_f32_e32 v170, v232, v170
	v_add_f32_e32 v170, v233, v170
	v_add_f32_e32 v170, v234, v170
	v_add_f32_e32 v170, v235, v170
	v_mfma_f32_32x32x16_bf16 v[64:79], v[132:135], v[84:87], v[64:79]
	v_add_f32_e32 v170, v236, v170
	v_add_f32_e32 v170, v237, v170
	v_add_f32_e32 v170, v238, v170
	v_add_f32_e32 v170, v239, v170
	v_mfma_f32_32x32x16_bf16 v[48:63], v[10:13], v[84:87], v[48:63]
	v_add_f32_e32 v170, v240, v170
	v_add_f32_e32 v170, v241, v170
	v_add_f32_e32 v170, v242, v170
	v_add_f32_e32 v170, v243, v170
	v_cvt_pk_bf16_f32 v228, v228, v229
	v_cvt_pk_bf16_f32 v229, v230, v231
	v_cvt_pk_bf16_f32 v230, v232, v233
	v_cvt_pk_bf16_f32 v231, v234, v235
	v_cvt_pk_bf16_f32 v232, v236, v237
	v_cvt_pk_bf16_f32 v233, v238, v239
	v_cvt_pk_bf16_f32 v234, v240, v241
	v_cvt_pk_bf16_f32 v235, v242, v243
	s_setprio 1
	v_mfma_f32_32x32x16_bf16 v[32:47], v[136:139], v[228:231], v[32:47]
	v_mfma_f32_32x32x16_bf16 v[16:31], v[128:131], v[228:231], v[16:31]
	v_mfma_f32_32x32x16_bf16 v[32:47], v[132:135], v[232:235], v[32:47]
	v_mfma_f32_32x32x16_bf16 v[16:31], v[10:13], v[232:235], v[16:31]
	s_setprio 0
	s_branch .LBB0_413
